# phase header: c_prog/c_hb lookups via scalar load + SALU instead of vector loads
# speedup vs baseline: 1.0074x; 1.0074x over previous
; #define LAS __attribute__((address_space(3)))
; __device__ __forceinline__ void final_rows(const bf16_t* hb, const float* g, float* outf, int gw, int NGW, int lane, int m_lo, int m_hi) {
;     f32x4 gv[4];
; #pragma unroll
;     for (int j = 0; j < 4; ++j) gv[j] = ((const f32x4*)g)[64 * j + lane];
;     for (int m0 = m_lo + gw; m0 < m_hi; m0 += 4 * NGW) {
;         u32x2 w[4][4];
; #pragma unroll
;         for (int r = 0; r < 4; ++r) { const int m = m0 + r * NGW < m_hi ? m0 + r * NGW : m_hi - 1; const u32x2* xr = (const u32x2*)(hb + (size_t)m * D) + lane;
; __global__ void __launch_bounds__(512, 2) fwd_kernel(Args args) {
;     ...
;         const int type = c_prog[ph][0], layer = c_prog[ph][1];
;         int zoff = 0; asm volatile("" : "+v"(zoff));
;         const volatile LAS unsigned* stw = (const volatile LAS unsigned*)(lds + 131072 + zoff);
;         const bool uni = __builtin_amdgcn_readfirstlane((int)stw[3]) != 0 && Gd == 256;
;         const int xrank = __builtin_amdgcn_readfirstlane((int)stw[2]), xcc = (int)xbar.x;
;         bf16_t* HBin = (bf16_t*)(ws + (c_hb_in[layer] ? WS_X1 : WS_X0)); bf16_t* HBmid = (bf16_t*)(ws + (c_hb_mid[layer] ? WS_X1 : WS_X0)); bf16_t* HBoth = (bf16_t*)(ws + (c_hb_mid[layer] ? WS_X0 : WS_X1));
.LBB0_8:
	s_mov_b64 s[60:61], s[78:79]
	v_mov_b32_e32 v170, v222
	s_load_dword s0, s[84:85], 0x0
	s_mov_b32 s5, s2
	v_mov_b32_e32 v0, v169
	v_readfirstlane_b32 s1, v170
	s_ashr_i32 s63, s1, 6
	s_waitcnt lgkmcnt(0)
	s_mov_b32 s6, s0
	s_load_dwordx4 s[68:71], s[60:61], 0xb8
	s_waitcnt lgkmcnt(0)
	v_writelane_b32 v255, s0, 30
	s_lshl_b32 s1, s5, 3
	v_add_u32_e32 v0, s3, v0
	ds_read_b32 v1, v0 offset:12
	ds_read_b32 v0, v0 offset:8
	s_lshl_b32 s77, s6, 3
	s_mov_b32 s8, s74
	s_mov_b32 s13, s95
	s_waitcnt lgkmcnt(1)
	v_readfirstlane_b32 s0, v1
	s_waitcnt lgkmcnt(0)
	v_readfirstlane_b32 s4, v0
	v_mov_b32_e32 v2, 0x19f80000
	v_mov_b32_e32 v3, 0x6c80000
	v_writelane_b32 v255, s4, 31
	v_writelane_b32 v255, s5, 32
	s_add_i32 s4, s1, s63
	v_writelane_b32 v255, s4, 33
	v_and_b32_e32 v126, 63, v170
	s_nop 0
	v_writelane_b32 v255, s5, 34
	s_add_u32 s4, s70, 0xac80000
	s_addc_u32 s5, s71, 0
	s_add_u32 s10, s70, 0xbf80000
	s_addc_u32 s11, s71, 0
	v_writelane_b32 v255, s10, 35
	s_add_u32 s1, s70, 0x1df80000
	s_nop 0
	v_writelane_b32 v255, s11, 36
	v_writelane_b32 v255, s1, 37
	s_addc_u32 s1, s71, 0
	v_writelane_b32 v255, s1, 38
	s_ashr_i32 s9, s74, 31
	s_mov_b32 s10, s74
	v_writelane_b32 v255, s10, 39
	s_lshl_b64 s[8:9], s[8:9], 1
	s_nop 0
	v_writelane_b32 v255, s11, 40
	s_getpc_b64 s[10:11]
	s_add_u32 s10, s10, c_prog@rel32@lo+4
	s_addc_u32 s11, s11, c_prog@rel32@hi+12
	s_and_b32 s7, s8, -4
	s_load_dword s7, s[10:11], s7
	s_waitcnt vmcnt(0) lgkmcnt(0)
	s_bitcmp1_b32 s8, 1
	s_cselect_b32 s1, 16, 0
	s_lshr_b32 s7, s7, s1
	s_and_b32 s7, s7, 0xffff
	s_and_b32 s1, 0xffff, s7
	s_lshr_b32 s12, s1, 8
	s_cmp_lg_u32 s0, 0
	s_cselect_b64 s[0:1], -1, 0
	s_cmpk_eq_i32 s6, 0x100
	s_cselect_b64 s[8:9], -1, 0
	s_cmp_eq_u32 s12, 1
	s_cselect_b32 s10, 1, 0
	s_add_i32 s11, s12, -1
	s_cmp_lt_u32 s11, 2
	s_cselect_b32 s11, 1, 0
	v_mov_b32_e32 v1, s10
	v_mov_b32_e32 v0, s11
	v_writelane_b32 v255, s12, 41
	s_and_b64 s[0:1], s[0:1], s[8:9]
	v_cmp_eq_u32_sdwa vcc, v1, v169 src0_sel:WORD_0 src1_sel:DWORD
	v_writelane_b32 v255, s13, 42
	v_writelane_b32 v255, s0, 43
	v_cndmask_b32_e32 v168, v2, v3, vcc
	v_lshl_add_u64 v[116:117], s[70:71], 0, v[168:169]
	v_writelane_b32 v255, s1, 44
	v_cmp_eq_u32_sdwa s[0:1], v0, v169 src0_sel:WORD_0 src1_sel:DWORD
	s_nop 1
	v_writelane_b32 v255, s0, 45
	s_nop 1
	v_writelane_b32 v255, s1, 46
	s_and_b64 s[0:1], s[0:1], exec
	s_cselect_b32 s0, s73, 0x19f80000
	s_add_u32 s0, s70, s0
	s_addc_u32 s1, s71, 0
	v_writelane_b32 v255, s0, 47
	s_nop 1
	v_writelane_b32 v255, s1, 48
	s_add_u32 s0, s70, 0x1e2c0000
	s_addc_u32 s1, s71, 0
	v_writelane_b32 v255, s0, 49
	s_nop 1
	v_writelane_b32 v255, s1, 50
	v_writelane_b32 v255, s60, 51
	s_and_b32 s0, s7, 0xff
	s_cmp_lt_i32 s0, 8
	v_writelane_b32 v255, s61, 52
	v_writelane_b32 v255, s0, 53
	s_cbranch_scc1 .LBB0_15
	s_and_b32 s0, 0xffff, s0
	v_writelane_b32 v255, s0, 54
	s_cmp_lt_i32 s0, 12
	s_mov_b64 s[10:11], -1
	s_cbranch_scc1 .LBB0_34
	v_readlane_b32 s0, v255, 54
	s_cmp_lt_i32 s0, 14
	s_mov_b64 s[8:9], -1
	s_cbranch_scc1 .LBB0_27
	s_mov_b64 s[36:37], -1
	s_cmp_lt_i32 s0, 15
	s_cbranch_scc1 .LBB0_24
	s_cmp_eq_u32 s0, 15
	s_cbranch_scc0 .LBB0_23
	v_readlane_b32 s0, v255, 31
	s_lshl_b32 s7, s0, 3
	v_readlane_b32 s0, v255, 17
	s_lshl_b32 s8, s0, 12
	v_readlane_b32 s12, v255, 43
	s_add_i32 s9, s8, 0x1000
	v_readlane_b32 s13, v255, 44
	s_and_b64 s[0:1], s[12:13], exec
	s_cselect_b32 s0, s9, 0x8000
	s_add_i32 s1, s63, s8
	s_add_i32 s1, s1, s7
	s_and_b64 s[8:9], s[12:13], exec
	v_readlane_b32 s8, v255, 33
	s_cselect_b32 s8, s1, s8
	s_load_dwordx2 s[10:11], s[60:61], 0x30
	s_cmp_ge_i32 s8, s0
	v_readlane_b32 s9, v255, 34
	s_waitcnt lgkmcnt(0)
	s_cbranch_scc1 .LBB0_23
	v_lshlrev_b32_e32 v168, 4, v126
	global_load_dwordx4 v[0:3], v168, s[10:11]
	global_load_dwordx4 v[4:7], v168, s[10:11] offset:1024
	global_load_dwordx4 v[8:11], v168, s[10:11] offset:2048
	global_load_dwordx4 v[12:15], v168, s[10:11] offset:3072
	v_cmp_lt_i32_e32 vcc, v229, v228
	v_readlane_b32 s10, v255, 43
	v_readlane_b32 s11, v255, 44
	v_cndmask_b32_e32 v18, v225, v229, vcc
	v_cmp_lt_i32_e32 vcc, v230, v228
	v_lshlrev_b32_e32 v70, 2, v18
	s_and_b64 s[10:11], s[10:11], exec
	v_cndmask_b32_e32 v18, v225, v230, vcc
	v_cmp_lt_i32_e32 vcc, v231, v228
	v_lshlrev_b32_e32 v71, 2, v18
	v_lshlrev_b32_e32 v16, 3, v126
	v_cndmask_b32_e32 v18, v225, v231, vcc
	v_cmp_lt_i32_e32 vcc, v232, v228
	v_lshlrev_b32_e32 v72, 2, v18
	v_mov_b32_e32 v17, v169
	v_cndmask_b32_e32 v18, v225, v232, vcc
	v_cmp_lt_i32_e32 vcc, v233, v228
	v_lshlrev_b32_e32 v73, 2, v18
	s_cselect_b32 s1, 0x100, s77
	v_cndmask_b32_e32 v18, v225, v233, vcc
	v_cmp_lt_i32_e32 vcc, v234, v228
	v_lshl_add_u64 v[16:17], s[70:71], 0, v[16:17]
	s_mov_b64 s[10:11], 0x19f80000
	v_lshlrev_b32_e32 v74, 2, v18
	v_cndmask_b32_e32 v18, v225, v234, vcc
	s_add_i32 s7, s0, -1
	v_lshl_add_u64 v[16:17], v[16:17], 0, s[10:11]
	v_lshlrev_b32_e32 v75, 2, v18
	v_lshl_add_u64 v[18:19], s[68:69], 0, v[168:169]
	s_lshl_b32 s16, s1, 1
	s_branch .LBB0_17
